# MoE weight transposes moved from phase 0 into mixer-phase work queue (nt loads/stores); phase-0 prefetch job-type compare fixed to use clamped tile index
# baseline (speedup 1.0000x reference)
_Z4mega6Params:
	s_add_u32 s58, s0, 0x120
	s_addc_u32 s59, s1, 0
	s_load_dwordx2 s[38:39], s[0:1], 0xe0
	s_load_dwordx4 s[4:7], s[0:1], 0xb8
	s_load_dwordx4 s[8:11], s[0:1], 0xa0
	s_load_dwordx2 s[28:29], s[0:1], 0x88
	s_load_dwordx4 s[20:23], s[0:1], 0x78
	s_load_dwordx2 s[30:31], s[0:1], 0x60
	v_writelane_b32 v254, s0, 0
	s_load_dwordx8 s[12:19], s[0:1], 0x0
	v_and_b32_e32 v216, 0x3ff, v0
	s_min_i32 s42, s2, 0x187f
	v_mov_b32_e32 v2, v216
	s_waitcnt lgkmcnt(0)
	v_mov_b32_e32 v1, s38
	v_mov_b32_e32 v3, s39
	v_mov_b32_e32 v4, s38
	v_mov_b32_e32 v5, s39
	s_cmpk_gt_i32 s2, 0x103f
	v_writelane_b32 v254, s1, 1
	s_nop 0
	v_readfirstlane_b32 s24, v4
	v_readfirstlane_b32 s25, v5
	v_readfirstlane_b32 s44, v1
	v_readfirstlane_b32 s45, v3
	s_cbranch_scc0 .LBB0_6
	s_cmpk_gt_u32 s2, 0x15bf
	s_cbranch_scc0 .LBB0_7
	s_cmpk_gt_i32 s2, 0x187f
	s_cbranch_scc0 .LBB0_8
	s_cmpk_gt_i32 s2, 0x507f
	s_cbranch_scc0 .LBB0_20
	s_add_i32 s3, s42, 0xaf80
	s_bfe_u32 s26, s3, 0x90007
	s_mulk_i32 s26, 0x2493
	s_lshr_b32 s33, s26, 16
	s_mul_i32 s26, s33, 0xe00000
	s_add_u32 s26, s6, s26
	s_mul_i32 s34, s33, 0x700000
	s_mulk_i32 s33, 0x380
	s_addc_u32 s27, s7, 0
	s_sub_i32 s3, s3, s33
	s_and_b32 s3, s3, 0xffff
	s_add_u32 s33, s44, s34
	s_addc_u32 s35, s45, 0
	s_add_u32 s34, s33, 0xa100000
	s_addc_u32 s35, s35, 0
	s_mov_b32 s46, 1
	s_cbranch_execz .LBB0_21
	s_mov_b64 s[36:37], 0xe00
	s_movk_i32 s33, 0x400
	s_mov_b32 s46, 0
	s_cbranch_execz .LBB0_9
	s_branch .LBB0_10

.LBB0_49:
	s_or_b64 exec, exec, s[40:41]
	s_waitcnt lgkmcnt(0)
	s_ashr_i32 s27, s26, 31
	s_cmpk_gt_i32 s2, 0x187f
	s_cbranch_scc1 .LBB0_106
	v_mov_b32_e32 v14, s38
	v_mov_b32_e32 v15, s39
	v_mov_b32_e32 v7, 0
	s_movk_i32 s48, 0x104
	s_movk_i32 s49, 0xffc0
	s_mov_b32 s50, s2
	s_branch .LBB0_53

.LBB0_52:
	s_or_b64 exec, exec, s[42:43]
	v_lshlrev_b32_e32 v4, 3, v6
	v_and_b32_e32 v6, 24, v4
	v_mul_u32_u24_e32 v4, 0x104, v6
	v_lshl_add_u32 v3, v3, 2, v4
	ds_read2_b32 v[4:5], v3 offset1:65
	ds_read2_b32 v[10:11], v3 offset0:130 offset1:195
	v_add_u32_e32 v8, 0x400, v3
	ds_read2_b32 v[12:13], v8 offset0:4 offset1:69
	ds_read2_b32 v[16:17], v8 offset0:134 offset1:199
	v_ashrrev_i32_e32 v18, 31, v1
	s_waitcnt lgkmcnt(3)
	v_cvt_pk_bf16_f32 v8, v4, v5
	s_waitcnt lgkmcnt(2)
	v_cvt_pk_bf16_f32 v9, v10, v11
	s_waitcnt lgkmcnt(1)
	v_cvt_pk_bf16_f32 v10, v12, v13
	v_mul_lo_u32 v12, s37, v1
	v_mul_lo_u32 v13, s36, v18
	v_mad_u64_u32 v[4:5], s[36:37], s36, v1, 0
	v_add_u32_e32 v1, 0x2000, v3
	s_waitcnt lgkmcnt(0)
	v_cvt_pk_bf16_f32 v11, v16, v17
	v_add3_u32 v5, v5, v13, v12
	ds_read2_b32 v[12:13], v1 offset0:32 offset1:97
	ds_read2_b32 v[16:17], v1 offset0:162 offset1:227
	v_add_u32_e32 v1, 0x2400, v3
	ds_read2_b32 v[18:19], v1 offset0:36 offset1:101
	ds_read2_b32 v[20:21], v1 offset0:166 offset1:231
	s_lshl_b32 s42, s47, 6
	s_ashr_i32 s43, s42, 31
	v_lshl_add_u64 v[4:5], v[4:5], 1, s[34:35]
	v_lshl_add_u64 v[4:5], s[42:43], 1, v[4:5]
	v_lshlrev_b32_e32 v6, 1, v6
	v_lshl_add_u64 v[4:5], v[4:5], 0, v[6:7]
	global_store_dwordx4 v[4:5], v[8:11], off
	s_cmpk_lt_i32 s50, 0x1880
	v_mov_b32_e32 v1, v25
	s_waitcnt lgkmcnt(3)
	v_cvt_pk_bf16_f32 v8, v12, v13
	s_waitcnt lgkmcnt(2)
	v_cvt_pk_bf16_f32 v9, v16, v17
	s_waitcnt lgkmcnt(1)
	v_cvt_pk_bf16_f32 v10, v18, v19
	s_waitcnt lgkmcnt(0)
	v_cvt_pk_bf16_f32 v11, v20, v21
	global_store_dwordx4 v[4:5], v[8:11], off offset:64
	v_mov_b32_e32 v3, v26
	v_mov_b32_e32 v5, v24
	v_mov_b32_e32 v4, v27
	v_mov_b32_e32 v11, v29
	v_mov_b32_e32 v12, v30
	v_mov_b32_e32 v10, v28
	v_mov_b32_e32 v13, v31
	v_mov_b32_e32 v17, v33
	v_mov_b32_e32 v18, v34
	v_mov_b32_e32 v16, v32
	v_mov_b32_e32 v19, v36
	v_mov_b32_e32 v21, v38
	v_mov_b32_e32 v22, v39
	v_mov_b32_e32 v20, v37
	v_mov_b32_e32 v23, v40
	s_mov_b32 s46, s53
	s_mov_b32 s47, s54
	s_mov_b32 s33, s52
	s_mov_b64 s[36:37], s[40:41]
	s_mov_b64 s[34:35], s[38:39]
	s_mov_b32 s3, s51
	s_barrier
	s_cbranch_scc0 .LBB0_106
.LBB0_53:
	s_add_i32 s50, s50, s26
	s_min_i32 s57, s50, 0x187f
	v_mov_b32_e32 v6, v14
	v_mov_b32_e32 v8, v15
	s_cmpk_gt_i32 s50, 0x103f
	v_readfirstlane_b32 s55, v6
	v_readfirstlane_b32 s56, v8
	s_mov_b64 s[44:45], -1
	s_cbranch_scc0 .LBB0_66
	s_cmpk_gt_u32 s50, 0x15bf
	s_cbranch_scc0 .LBB0_60
	s_cmpk_gt_u32 s57, 0x187f
	s_cbranch_scc0 .LBB0_61
	s_cmpk_gt_u32 s50, 0x507f
	s_mov_b64 s[40:41], -1
	s_cbranch_scc0 .LBB0_58
	s_add_i32 s40, s57, 0xaf80
	s_bfe_u32 s38, s40, 0x90007
	s_mulk_i32 s38, 0x2493
	s_lshr_b32 s41, s38, 16
	s_mul_i32 s38, s41, 0xe00000
	s_add_u32 s42, s6, s38
	s_addc_u32 s43, s7, 0
	s_mul_i32 s38, s41, 0x700000
	s_add_u32 s38, s55, s38
	s_addc_u32 s39, s56, 0
	s_add_u32 s38, s38, 0xa100000
	s_mulk_i32 s41, 0x380
	s_addc_u32 s39, s39, 0
	s_sub_i32 s40, s40, s41
	s_and_b32 s51, s40, 0xffff
	s_mov_b64 s[40:41], 0

.LBB0_429:
	v_writelane_b32 v255, s48, 42
	v_writelane_b32 v255, s43, 43
	s_or_b64 exec, exec, s[0:1]
	v_readlane_b32 s4, v254, 45
	s_lshl_b32 s0, s82, 5
	v_readlane_b32 s5, v254, 46
	s_mov_b32 s1, s73
	s_lshl_b32 s72, s82, 6
	v_readlane_b32 s6, v254, 47
	s_lshl_b64 s[4:5], s[0:1], 2
	v_readlane_b32 s12, v254, 62
	v_readlane_b32 s7, v254, 48
	v_readlane_b32 s13, v254, 63
	s_add_u32 s6, s12, s4
	v_readlane_b32 s14, v255, 0
	s_addc_u32 s7, s13, s5
	v_readlane_b32 s15, v255, 1
	s_add_u32 s2, s14, s4
	v_readlane_b32 s10, v254, 51
	v_readlane_b32 s11, v254, 52
	v_readlane_b32 s16, v255, 2
	s_addc_u32 s3, s15, s5
	v_mov_b32_e32 v28, v216
	v_mov_b32_e32 v0, s10
	v_mov_b32_e32 v1, s11
	v_readlane_b32 s17, v255, 3
	s_add_u32 s0, s16, s4
	s_barrier
	v_readlane_b32 s8, v254, 49
	v_readlane_b32 s9, v254, 50
	v_readlane_b32 s18, v255, 4
	s_addc_u32 s1, s17, s5
	v_readfirstlane_b32 s8, v0
	v_readfirstlane_b32 s9, v1
	v_readlane_b32 s19, v255, 5
	global_load_dwordx4 v[0:3], v179, s[6:7] offset:48
	global_load_dwordx4 v[4:7], v179, s[6:7] offset:32
	global_load_dwordx4 v[8:11], v179, s[6:7] offset:16
	global_load_dwordx4 v[12:15], v179, s[6:7]
	global_load_dwordx4 v[16:19], v179, s[2:3] offset:48
	global_load_dwordx4 v[20:23], v179, s[2:3] offset:32
	global_load_dwordx4 v[24:27], v179, s[2:3] offset:16
	global_load_dwordx4 v[30:33], v179, s[2:3]
	s_add_u32 s4, s18, s4
	s_addc_u32 s5, s19, s5
	global_load_dwordx4 v[34:37], v179, s[0:1] offset:48
	global_load_dwordx4 v[38:41], v179, s[0:1] offset:32
	global_load_dwordx4 v[42:45], v179, s[0:1] offset:16
	global_load_dwordx4 v[46:49], v179, s[0:1]
	global_load_dwordx4 v[50:53], v179, s[4:5] offset:48
	global_load_dwordx4 v[54:57], v179, s[4:5] offset:32
	global_load_dwordx4 v[58:61], v179, s[4:5] offset:16
	global_load_dwordx4 v[62:65], v179, s[4:5]
	v_readlane_b32 s20, v255, 6
	v_readlane_b32 s21, v255, 7
	v_readlane_b32 s22, v255, 8
	v_readlane_b32 s23, v255, 9
	v_readlane_b32 s24, v255, 10
	v_readlane_b32 s25, v255, 11
	v_readlane_b32 s26, v255, 12
	v_readlane_b32 s27, v255, 13
	s_waitcnt vmcnt(8)
	v_fma_f32 v30, v12, v30, 0
	v_fmac_f32_e32 v30, v13, v31
	v_fmac_f32_e32 v30, v14, v32
	v_fmac_f32_e32 v30, v15, v33
	s_waitcnt vmcnt(0)
	v_fma_f32 v29, v46, v62, 0
	v_fmac_f32_e32 v29, v47, v63
	v_fmac_f32_e32 v29, v48, v64
	v_fmac_f32_e32 v30, v8, v24
	v_fmac_f32_e32 v29, v49, v65
	v_fmac_f32_e32 v30, v9, v25
	v_fmac_f32_e32 v29, v42, v58
	v_fmac_f32_e32 v30, v10, v26
	v_fmac_f32_e32 v29, v43, v59
	v_fmac_f32_e32 v30, v11, v27
	v_fmac_f32_e32 v29, v44, v60
	v_fmac_f32_e32 v30, v4, v20
	v_fmac_f32_e32 v29, v45, v61
	v_fmac_f32_e32 v30, v5, v21
	v_fmac_f32_e32 v29, v38, v54
	v_fmac_f32_e32 v30, v6, v22
	v_fmac_f32_e32 v29, v39, v55
	v_fmac_f32_e32 v30, v7, v23
	v_fmac_f32_e32 v29, v40, v56
	v_fmac_f32_e32 v30, v0, v16
	v_fmac_f32_e32 v29, v41, v57
	v_fmac_f32_e32 v30, v1, v17
	v_fmac_f32_e32 v29, v34, v50
	v_fmac_f32_e32 v30, v2, v18
	v_fmac_f32_e32 v29, v35, v51
	v_fmac_f32_e32 v30, v3, v19
	global_load_dwordx4 v[0:3], v179, s[6:7] offset:112
	global_load_dwordx4 v[8:11], v179, s[6:7] offset:96
	global_load_dwordx4 v[16:19], v179, s[6:7] offset:80
	global_load_dwordx4 v[24:27], v179, s[6:7] offset:64
	global_load_dwordx4 v[4:7], v179, s[2:3] offset:112
	global_load_dwordx4 v[12:15], v179, s[2:3] offset:96
	global_load_dwordx4 v[20:23], v179, s[2:3] offset:80
	global_load_dwordx4 v[32:35], v179, s[2:3] offset:64
	v_fmac_f32_e32 v29, v36, v52
	v_fmac_f32_e32 v29, v37, v53
	global_load_dwordx4 v[36:39], v179, s[0:1] offset:112
	global_load_dwordx4 v[40:43], v179, s[0:1] offset:96
	global_load_dwordx4 v[44:47], v179, s[0:1] offset:80
	global_load_dwordx4 v[48:51], v179, s[0:1] offset:64
	global_load_dwordx4 v[52:55], v179, s[4:5] offset:112
	global_load_dwordx4 v[56:59], v179, s[4:5] offset:96
	global_load_dwordx4 v[60:63], v179, s[4:5] offset:80
	global_load_dwordx4 v[64:67], v179, s[4:5] offset:64
	s_mov_b32 s0, s82
	v_writelane_b32 v255, s0, 44
	v_readlane_b32 s2, v254, 0
	v_readlane_b32 s3, v254, 1
	v_writelane_b32 v255, s1, 45
	s_lshl_b64 s[0:1], s[82:83], 2
	s_add_u32 s6, s2, s0
	s_addc_u32 s7, s3, s1
	s_lshl_b64 s[2:3], s[72:73], 2
	s_add_u32 s82, s20, s2
	s_mov_b32 s2, 0x3fb8aa3b
	s_addc_u32 s83, s21, s3
	s_mov_b32 s3, 0xc2ce8ed0
	s_mov_b32 s4, 0x42b17218
	v_writelane_b32 v255, s6, 46
	s_add_u32 s0, s8, s0
	s_addc_u32 s1, s9, s1
	s_add_u32 s0, s0, 0x1d200000
	v_writelane_b32 v255, s7, 47
	s_addc_u32 s1, s1, 0
	v_writelane_b32 v255, s0, 48
	s_waitcnt vmcnt(8)
	v_fmac_f32_e32 v30, v24, v32
	v_fmac_f32_e32 v30, v25, v33
	v_fmac_f32_e32 v30, v26, v34
	v_fmac_f32_e32 v30, v27, v35
	v_fmac_f32_e32 v30, v16, v20
	v_fmac_f32_e32 v30, v17, v21
	v_fmac_f32_e32 v30, v18, v22
	v_fmac_f32_e32 v30, v19, v23
	s_waitcnt vmcnt(0)
	v_fmac_f32_e32 v29, v48, v64
	v_fmac_f32_e32 v30, v8, v12
	v_fmac_f32_e32 v29, v49, v65
	v_fmac_f32_e32 v30, v9, v13
	v_fmac_f32_e32 v29, v50, v66
	v_fmac_f32_e32 v30, v10, v14
	v_fmac_f32_e32 v29, v51, v67
	v_fmac_f32_e32 v30, v11, v15
	v_fmac_f32_e32 v29, v44, v60
	v_fmac_f32_e32 v30, v0, v4
	v_fmac_f32_e32 v29, v45, v61
	v_fmac_f32_e32 v30, v1, v5
	v_fmac_f32_e32 v29, v46, v62
	v_fmac_f32_e32 v30, v2, v6
	v_fmac_f32_e32 v29, v47, v63
	v_fmac_f32_e32 v30, v3, v7
	v_fmac_f32_e32 v29, v40, v56
	v_mul_f32_e32 v0, 0x3fb8aa3b, v30
	v_fmac_f32_e32 v29, v41, v57
	v_fma_f32 v1, v30, s2, -v0
	v_rndne_f32_e32 v2, v0
	v_fmac_f32_e32 v29, v42, v58
	v_fmac_f32_e32 v1, 0x32a5705f, v30
	v_sub_f32_e32 v0, v0, v2
	v_fmac_f32_e32 v29, v43, v59
	v_add_f32_e32 v0, v0, v1
	v_fmac_f32_e32 v29, v36, v52
	v_exp_f32_e32 v0, v0
	v_cvt_i32_f32_e32 v1, v2
	v_fmac_f32_e32 v29, v37, v53
	v_fmac_f32_e32 v29, v38, v54
	v_fmac_f32_e32 v29, v39, v55
	v_ldexp_f32 v0, v0, v1
	v_mul_f32_e32 v1, 0x3fb8aa3b, v29
	v_fma_f32 v2, v29, s2, -v1
	v_rndne_f32_e32 v3, v1
	v_fmac_f32_e32 v2, 0x32a5705f, v29
	v_sub_f32_e32 v1, v1, v3
	v_add_f32_e32 v1, v1, v2
	v_exp_f32_e32 v1, v1
	v_cvt_i32_f32_e32 v2, v3
	v_cmp_ngt_f32_e32 vcc, s3, v30
	s_load_dword s2, s[6:7], 0x118
	v_cmp_eq_u32_e64 s[6:7], 0, v28
	v_cndmask_b32_e32 v0, 0, v0, vcc
	v_cmp_nlt_f32_e32 vcc, s4, v30
	v_ldexp_f32 v1, v1, v2
	v_writelane_b32 v255, s1, 49
	v_cndmask_b32_e32 v0, v228, v0, vcc
	v_cmp_ngt_f32_e32 vcc, s3, v29
	s_nop 1
	v_cndmask_b32_e32 v1, 0, v1, vcc
	v_cmp_nlt_f32_e32 vcc, s4, v29
	s_nop 1
	v_cndmask_b32_e32 v1, v228, v1, vcc
	v_sub_f32_e32 v0, v0, v1
	s_waitcnt lgkmcnt(0)
	v_add_f32_e32 v147, s2, v0
	s_branch .LBB0_433
.Ltramp_end:
	s_branch .LBB0_1114
.Ltramp_153:
	s_branch .LBB0_153
.Ltrx_item:
	v_readlane_b32 s0, v254, 0
	v_readlane_b32 s1, v254, 1
	v_readlane_b32 s2, v255, 44
	v_readlane_b32 s10, v254, 51
	v_readlane_b32 s11, v254, 52
	s_nop 7
	s_mul_i32 s2, s2, 0x540
	s_add_i32 s2, s2, s95
	s_sub_i32 s2, s2, 0xb20
	s_cmpk_lt_u32 s2, 0x700
	s_cbranch_scc0 .Ltrx_b
	s_load_dwordx2 s[8:9], s[0:1], 0xb8
	s_and_b32 s3, s2, 7
	s_bfe_u32 s4, s2, 0x40003
	s_lshr_b32 s2, s2, 7
	s_waitcnt lgkmcnt(0)
	s_mul_i32 s0, s3, 0x1c00000
	s_add_u32 s8, s8, s0
	s_addc_u32 s9, s9, 0
	s_mul_i32 s0, s4, 0x1c0000
	s_lshl_b32 s1, s2, 11
	s_add_u32 s0, s0, s1
	s_add_u32 s8, s8, s0
	s_addc_u32 s9, s9, 0
	s_add_u32 s10, s10, 0x3100000
	s_addc_u32 s11, s11, 0
	s_mul_i32 s0, s3, 0xe00000
	s_lshl_b32 s1, s4, 7
	s_add_u32 s0, s0, s1
	s_add_u32 s10, s10, s0
	s_addc_u32 s11, s11, 0
	s_cmpk_lt_u32 s2, 7
	s_cselect_b32 s0, 0, 32
	s_cselect_b32 s1, 0, 7
	s_sub_i32 s2, s2, s1
	s_lshl_b32 s2, s2, 10
	s_add_i32 s2, s2, s0
	s_lshl_b32 s2, s2, 11
	s_add_u32 s10, s10, s2
	s_addc_u32 s11, s11, 0
	v_and_b32_e32 v1, 63, v216
	v_lshrrev_b32_e32 v2, 6, v216
	v_mul_u32_u24_e32 v3, 0x41, v2
	v_add_lshl_u32 v3, v3, v1, 2
	v_and_b32_e32 v6, 3, v216
	v_lshrrev_b32_e32 v7, 2, v216
	v_mul_u32_u24_e32 v4, 0x208, v6
	v_add_lshl_u32 v4, v4, v7, 2
	v_lshrrev_b32_e32 v5, 5, v7
	v_and_b32_e32 v24, 31, v7
	v_lshl_add_u32 v5, v5, 6, v24
	v_lshlrev_b32_e32 v5, 11, v5
	v_lshl_add_u32 v5, v6, 4, v5
	v_mul_u32_u24_e32 v8, 0x7000, v2
	v_lshl_add_u32 v8, v1, 2, v8
	v_add_u32_e32 v9, 0x1c000, v8
	v_add_u32_e32 v10, 0x1c000, v9
	v_add_u32_e32 v11, 0x1c000, v10
	v_add_u32_e32 v12, 0x1c000, v11
	v_add_u32_e32 v13, 0x1c000, v12
	v_add_u32_e32 v14, 0x1c000, v13
	v_add_u32_e32 v15, 0x1c000, v14
	v_add_u32_e32 v16, 0x1c000, v15
	v_add_u32_e32 v17, 0x1c000, v16
	v_add_u32_e32 v18, 0x1c000, v17
	v_add_u32_e32 v19, 0x1c000, v18
	v_add_u32_e32 v20, 0x1c000, v19
	v_add_u32_e32 v21, 0x1c000, v20
	v_add_u32_e32 v22, 0x1c000, v21
	v_add_u32_e32 v23, 0x1c000, v22
	global_load_dword v32, v8, s[8:9] nt
	global_load_dword v33, v9, s[8:9] nt
	global_load_dword v34, v10, s[8:9] nt
	global_load_dword v35, v11, s[8:9] nt
	global_load_dword v36, v12, s[8:9] nt
	global_load_dword v37, v13, s[8:9] nt
	global_load_dword v38, v14, s[8:9] nt
	global_load_dword v39, v15, s[8:9] nt
	global_load_dword v40, v16, s[8:9] nt
	global_load_dword v41, v17, s[8:9] nt
	global_load_dword v42, v18, s[8:9] nt
	global_load_dword v43, v19, s[8:9] nt
	global_load_dword v44, v20, s[8:9] nt
	global_load_dword v45, v21, s[8:9] nt
	global_load_dword v46, v22, s[8:9] nt
	global_load_dword v47, v23, s[8:9] nt
	global_load_dword v48, v8, s[8:9] offset:256 nt
	global_load_dword v49, v9, s[8:9] offset:256 nt
	global_load_dword v50, v10, s[8:9] offset:256 nt
	global_load_dword v51, v11, s[8:9] offset:256 nt
	global_load_dword v52, v12, s[8:9] offset:256 nt
	global_load_dword v53, v13, s[8:9] offset:256 nt
	global_load_dword v54, v14, s[8:9] offset:256 nt
	global_load_dword v55, v15, s[8:9] offset:256 nt
	global_load_dword v56, v16, s[8:9] offset:256 nt
	global_load_dword v57, v17, s[8:9] offset:256 nt
	global_load_dword v58, v18, s[8:9] offset:256 nt
	global_load_dword v59, v19, s[8:9] offset:256 nt
	global_load_dword v60, v20, s[8:9] offset:256 nt
	global_load_dword v61, v21, s[8:9] offset:256 nt
	global_load_dword v62, v22, s[8:9] offset:256 nt
	global_load_dword v63, v23, s[8:9] offset:256 nt
	s_waitcnt vmcnt(16)
	ds_write_b32 v3, v32
	ds_write_b32 v3, v33 offset:1040
	ds_write_b32 v3, v34 offset:2080
	ds_write_b32 v3, v35 offset:3120
	ds_write_b32 v3, v36 offset:4160
	ds_write_b32 v3, v37 offset:5200
	ds_write_b32 v3, v38 offset:6240
	ds_write_b32 v3, v39 offset:7280
	ds_write_b32 v3, v40 offset:8320
	ds_write_b32 v3, v41 offset:9360
	ds_write_b32 v3, v42 offset:10400
	ds_write_b32 v3, v43 offset:11440
	ds_write_b32 v3, v44 offset:12480
	ds_write_b32 v3, v45 offset:13520
	ds_write_b32 v3, v46 offset:14560
	ds_write_b32 v3, v47 offset:15600
	s_waitcnt lgkmcnt(0)
	s_barrier
	ds_read_b32 v64, v4
	ds_read_b32 v65, v4 offset:260
	ds_read_b32 v66, v4 offset:520
	ds_read_b32 v67, v4 offset:780
	ds_read_b32 v68, v4 offset:1040
	ds_read_b32 v69, v4 offset:1300
	ds_read_b32 v70, v4 offset:1560
	ds_read_b32 v71, v4 offset:1820
	ds_read_b32 v72, v4 offset:8320
	ds_read_b32 v73, v4 offset:8580
	ds_read_b32 v74, v4 offset:8840
	ds_read_b32 v75, v4 offset:9100
	ds_read_b32 v76, v4 offset:9360
	ds_read_b32 v77, v4 offset:9620
	ds_read_b32 v78, v4 offset:9880
	ds_read_b32 v79, v4 offset:10140
	s_waitcnt lgkmcnt(0)
	v_cvt_pk_bf16_f32 v80, v64, v65
	v_cvt_pk_bf16_f32 v81, v66, v67
	v_cvt_pk_bf16_f32 v82, v68, v69
	v_cvt_pk_bf16_f32 v83, v70, v71
	v_cvt_pk_bf16_f32 v84, v72, v73
	v_cvt_pk_bf16_f32 v85, v74, v75
	v_cvt_pk_bf16_f32 v86, v76, v77
	v_cvt_pk_bf16_f32 v87, v78, v79
	global_store_dwordx4 v5, v[80:83], s[10:11] nt
	global_store_dwordx4 v5, v[84:87], s[10:11] offset:64 nt
	s_add_u32 s10, s10, 0x40000
	s_addc_u32 s11, s11, 0
	global_load_dword v32, v8, s[8:9] offset:512 nt
	global_load_dword v33, v9, s[8:9] offset:512 nt
	global_load_dword v34, v10, s[8:9] offset:512 nt
	global_load_dword v35, v11, s[8:9] offset:512 nt
	global_load_dword v36, v12, s[8:9] offset:512 nt
	global_load_dword v37, v13, s[8:9] offset:512 nt
	global_load_dword v38, v14, s[8:9] offset:512 nt
	global_load_dword v39, v15, s[8:9] offset:512 nt
	global_load_dword v40, v16, s[8:9] offset:512 nt
	global_load_dword v41, v17, s[8:9] offset:512 nt
	global_load_dword v42, v18, s[8:9] offset:512 nt
	global_load_dword v43, v19, s[8:9] offset:512 nt
	global_load_dword v44, v20, s[8:9] offset:512 nt
	global_load_dword v45, v21, s[8:9] offset:512 nt
	global_load_dword v46, v22, s[8:9] offset:512 nt
	global_load_dword v47, v23, s[8:9] offset:512 nt
	s_waitcnt vmcnt(18)
	ds_write_b32 v3, v48 offset:16640
	ds_write_b32 v3, v49 offset:17680
	ds_write_b32 v3, v50 offset:18720
	ds_write_b32 v3, v51 offset:19760
	ds_write_b32 v3, v52 offset:20800
	ds_write_b32 v3, v53 offset:21840
	ds_write_b32 v3, v54 offset:22880
	ds_write_b32 v3, v55 offset:23920
	ds_write_b32 v3, v56 offset:24960
	ds_write_b32 v3, v57 offset:26000
	ds_write_b32 v3, v58 offset:27040
	ds_write_b32 v3, v59 offset:28080
	ds_write_b32 v3, v60 offset:29120
	ds_write_b32 v3, v61 offset:30160
	ds_write_b32 v3, v62 offset:31200
	ds_write_b32 v3, v63 offset:32240
	s_waitcnt lgkmcnt(0)
	s_barrier
	ds_read_b32 v64, v4 offset:16640
	ds_read_b32 v65, v4 offset:16900
	ds_read_b32 v66, v4 offset:17160
	ds_read_b32 v67, v4 offset:17420
	ds_read_b32 v68, v4 offset:17680
	ds_read_b32 v69, v4 offset:17940
	ds_read_b32 v70, v4 offset:18200
	ds_read_b32 v71, v4 offset:18460
	ds_read_b32 v72, v4 offset:24960
	ds_read_b32 v73, v4 offset:25220
	ds_read_b32 v74, v4 offset:25480
	ds_read_b32 v75, v4 offset:25740
	ds_read_b32 v76, v4 offset:26000
	ds_read_b32 v77, v4 offset:26260
	ds_read_b32 v78, v4 offset:26520
	ds_read_b32 v79, v4 offset:26780
	s_waitcnt lgkmcnt(0)
	v_cvt_pk_bf16_f32 v80, v64, v65
	v_cvt_pk_bf16_f32 v81, v66, v67
	v_cvt_pk_bf16_f32 v82, v68, v69
	v_cvt_pk_bf16_f32 v83, v70, v71
	v_cvt_pk_bf16_f32 v84, v72, v73
	v_cvt_pk_bf16_f32 v85, v74, v75
	v_cvt_pk_bf16_f32 v86, v76, v77
	v_cvt_pk_bf16_f32 v87, v78, v79
	global_store_dwordx4 v5, v[80:83], s[10:11] nt
	global_store_dwordx4 v5, v[84:87], s[10:11] offset:64 nt
	s_add_u32 s10, s10, 0x40000
	s_addc_u32 s11, s11, 0
	global_load_dword v48, v8, s[8:9] offset:768 nt
	global_load_dword v49, v9, s[8:9] offset:768 nt
	global_load_dword v50, v10, s[8:9] offset:768 nt
	global_load_dword v51, v11, s[8:9] offset:768 nt
	global_load_dword v52, v12, s[8:9] offset:768 nt
	global_load_dword v53, v13, s[8:9] offset:768 nt
	global_load_dword v54, v14, s[8:9] offset:768 nt
	global_load_dword v55, v15, s[8:9] offset:768 nt
	global_load_dword v56, v16, s[8:9] offset:768 nt
	global_load_dword v57, v17, s[8:9] offset:768 nt
	global_load_dword v58, v18, s[8:9] offset:768 nt
	global_load_dword v59, v19, s[8:9] offset:768 nt
	global_load_dword v60, v20, s[8:9] offset:768 nt
	global_load_dword v61, v21, s[8:9] offset:768 nt
	global_load_dword v62, v22, s[8:9] offset:768 nt
	global_load_dword v63, v23, s[8:9] offset:768 nt
	s_waitcnt vmcnt(18)
	ds_write_b32 v3, v32
	ds_write_b32 v3, v33 offset:1040
	ds_write_b32 v3, v34 offset:2080
	ds_write_b32 v3, v35 offset:3120
	ds_write_b32 v3, v36 offset:4160
	ds_write_b32 v3, v37 offset:5200
	ds_write_b32 v3, v38 offset:6240
	ds_write_b32 v3, v39 offset:7280
	ds_write_b32 v3, v40 offset:8320
	ds_write_b32 v3, v41 offset:9360
	ds_write_b32 v3, v42 offset:10400
	ds_write_b32 v3, v43 offset:11440
	ds_write_b32 v3, v44 offset:12480
	ds_write_b32 v3, v45 offset:13520
	ds_write_b32 v3, v46 offset:14560
	ds_write_b32 v3, v47 offset:15600
	s_waitcnt lgkmcnt(0)
	s_barrier
	ds_read_b32 v64, v4
	ds_read_b32 v65, v4 offset:260
	ds_read_b32 v66, v4 offset:520
	ds_read_b32 v67, v4 offset:780
	ds_read_b32 v68, v4 offset:1040
	ds_read_b32 v69, v4 offset:1300
	ds_read_b32 v70, v4 offset:1560
	ds_read_b32 v71, v4 offset:1820
	ds_read_b32 v72, v4 offset:8320
	ds_read_b32 v73, v4 offset:8580
	ds_read_b32 v74, v4 offset:8840
	ds_read_b32 v75, v4 offset:9100
	ds_read_b32 v76, v4 offset:9360
	ds_read_b32 v77, v4 offset:9620
	ds_read_b32 v78, v4 offset:9880
	ds_read_b32 v79, v4 offset:10140
	s_waitcnt lgkmcnt(0)
	v_cvt_pk_bf16_f32 v80, v64, v65
	v_cvt_pk_bf16_f32 v81, v66, v67
	v_cvt_pk_bf16_f32 v82, v68, v69
	v_cvt_pk_bf16_f32 v83, v70, v71
	v_cvt_pk_bf16_f32 v84, v72, v73
	v_cvt_pk_bf16_f32 v85, v74, v75
	v_cvt_pk_bf16_f32 v86, v76, v77
	v_cvt_pk_bf16_f32 v87, v78, v79
	global_store_dwordx4 v5, v[80:83], s[10:11] nt
	global_store_dwordx4 v5, v[84:87], s[10:11] offset:64 nt
	s_add_u32 s10, s10, 0x40000
	s_addc_u32 s11, s11, 0
	global_load_dword v32, v8, s[8:9] offset:1024 nt
	global_load_dword v33, v9, s[8:9] offset:1024 nt
	global_load_dword v34, v10, s[8:9] offset:1024 nt
	global_load_dword v35, v11, s[8:9] offset:1024 nt
	global_load_dword v36, v12, s[8:9] offset:1024 nt
	global_load_dword v37, v13, s[8:9] offset:1024 nt
	global_load_dword v38, v14, s[8:9] offset:1024 nt
	global_load_dword v39, v15, s[8:9] offset:1024 nt
	global_load_dword v40, v16, s[8:9] offset:1024 nt
	global_load_dword v41, v17, s[8:9] offset:1024 nt
	global_load_dword v42, v18, s[8:9] offset:1024 nt
	global_load_dword v43, v19, s[8:9] offset:1024 nt
	global_load_dword v44, v20, s[8:9] offset:1024 nt
	global_load_dword v45, v21, s[8:9] offset:1024 nt
	global_load_dword v46, v22, s[8:9] offset:1024 nt
	global_load_dword v47, v23, s[8:9] offset:1024 nt
	s_waitcnt vmcnt(18)
	ds_write_b32 v3, v48 offset:16640
	ds_write_b32 v3, v49 offset:17680
	ds_write_b32 v3, v50 offset:18720
	ds_write_b32 v3, v51 offset:19760
	ds_write_b32 v3, v52 offset:20800
	ds_write_b32 v3, v53 offset:21840
	ds_write_b32 v3, v54 offset:22880
	ds_write_b32 v3, v55 offset:23920
	ds_write_b32 v3, v56 offset:24960
	ds_write_b32 v3, v57 offset:26000
	ds_write_b32 v3, v58 offset:27040
	ds_write_b32 v3, v59 offset:28080
	ds_write_b32 v3, v60 offset:29120
	ds_write_b32 v3, v61 offset:30160
	ds_write_b32 v3, v62 offset:31200
	ds_write_b32 v3, v63 offset:32240
	s_waitcnt lgkmcnt(0)
	s_barrier
	ds_read_b32 v64, v4 offset:16640
	ds_read_b32 v65, v4 offset:16900
	ds_read_b32 v66, v4 offset:17160
	ds_read_b32 v67, v4 offset:17420
	ds_read_b32 v68, v4 offset:17680
	ds_read_b32 v69, v4 offset:17940
	ds_read_b32 v70, v4 offset:18200
	ds_read_b32 v71, v4 offset:18460
	ds_read_b32 v72, v4 offset:24960
	ds_read_b32 v73, v4 offset:25220
	ds_read_b32 v74, v4 offset:25480
	ds_read_b32 v75, v4 offset:25740
	ds_read_b32 v76, v4 offset:26000
	ds_read_b32 v77, v4 offset:26260
	ds_read_b32 v78, v4 offset:26520
	ds_read_b32 v79, v4 offset:26780
	s_waitcnt lgkmcnt(0)
	v_cvt_pk_bf16_f32 v80, v64, v65
	v_cvt_pk_bf16_f32 v81, v66, v67
	v_cvt_pk_bf16_f32 v82, v68, v69
	v_cvt_pk_bf16_f32 v83, v70, v71
	v_cvt_pk_bf16_f32 v84, v72, v73
	v_cvt_pk_bf16_f32 v85, v74, v75
	v_cvt_pk_bf16_f32 v86, v76, v77
	v_cvt_pk_bf16_f32 v87, v78, v79
	global_store_dwordx4 v5, v[80:83], s[10:11] nt
	global_store_dwordx4 v5, v[84:87], s[10:11] offset:64 nt
	s_add_u32 s10, s10, 0x40000
	s_addc_u32 s11, s11, 0
	global_load_dword v48, v8, s[8:9] offset:1280 nt
	global_load_dword v49, v9, s[8:9] offset:1280 nt
	global_load_dword v50, v10, s[8:9] offset:1280 nt
	global_load_dword v51, v11, s[8:9] offset:1280 nt
	global_load_dword v52, v12, s[8:9] offset:1280 nt
	global_load_dword v53, v13, s[8:9] offset:1280 nt
	global_load_dword v54, v14, s[8:9] offset:1280 nt
	global_load_dword v55, v15, s[8:9] offset:1280 nt
	global_load_dword v56, v16, s[8:9] offset:1280 nt
	global_load_dword v57, v17, s[8:9] offset:1280 nt
	global_load_dword v58, v18, s[8:9] offset:1280 nt
	global_load_dword v59, v19, s[8:9] offset:1280 nt
	global_load_dword v60, v20, s[8:9] offset:1280 nt
	global_load_dword v61, v21, s[8:9] offset:1280 nt
	global_load_dword v62, v22, s[8:9] offset:1280 nt
	global_load_dword v63, v23, s[8:9] offset:1280 nt
	s_waitcnt vmcnt(18)
	ds_write_b32 v3, v32
	ds_write_b32 v3, v33 offset:1040
	ds_write_b32 v3, v34 offset:2080
	ds_write_b32 v3, v35 offset:3120
	ds_write_b32 v3, v36 offset:4160
	ds_write_b32 v3, v37 offset:5200
	ds_write_b32 v3, v38 offset:6240
	ds_write_b32 v3, v39 offset:7280
	ds_write_b32 v3, v40 offset:8320
	ds_write_b32 v3, v41 offset:9360
	ds_write_b32 v3, v42 offset:10400
	ds_write_b32 v3, v43 offset:11440
	ds_write_b32 v3, v44 offset:12480
	ds_write_b32 v3, v45 offset:13520
	ds_write_b32 v3, v46 offset:14560
	ds_write_b32 v3, v47 offset:15600
	s_waitcnt lgkmcnt(0)
	s_barrier
	ds_read_b32 v64, v4
	ds_read_b32 v65, v4 offset:260
	ds_read_b32 v66, v4 offset:520
	ds_read_b32 v67, v4 offset:780
	ds_read_b32 v68, v4 offset:1040
	ds_read_b32 v69, v4 offset:1300
	ds_read_b32 v70, v4 offset:1560
	ds_read_b32 v71, v4 offset:1820
	ds_read_b32 v72, v4 offset:8320
	ds_read_b32 v73, v4 offset:8580
	ds_read_b32 v74, v4 offset:8840
	ds_read_b32 v75, v4 offset:9100
	ds_read_b32 v76, v4 offset:9360
	ds_read_b32 v77, v4 offset:9620
	ds_read_b32 v78, v4 offset:9880
	ds_read_b32 v79, v4 offset:10140
	s_waitcnt lgkmcnt(0)
	v_cvt_pk_bf16_f32 v80, v64, v65
	v_cvt_pk_bf16_f32 v81, v66, v67
	v_cvt_pk_bf16_f32 v82, v68, v69
	v_cvt_pk_bf16_f32 v83, v70, v71
	v_cvt_pk_bf16_f32 v84, v72, v73
	v_cvt_pk_bf16_f32 v85, v74, v75
	v_cvt_pk_bf16_f32 v86, v76, v77
	v_cvt_pk_bf16_f32 v87, v78, v79
	global_store_dwordx4 v5, v[80:83], s[10:11] nt
	global_store_dwordx4 v5, v[84:87], s[10:11] offset:64 nt
	s_add_u32 s10, s10, 0x40000
	s_addc_u32 s11, s11, 0
	global_load_dword v32, v8, s[8:9] offset:1536 nt
	global_load_dword v33, v9, s[8:9] offset:1536 nt
	global_load_dword v34, v10, s[8:9] offset:1536 nt
	global_load_dword v35, v11, s[8:9] offset:1536 nt
	global_load_dword v36, v12, s[8:9] offset:1536 nt
	global_load_dword v37, v13, s[8:9] offset:1536 nt
	global_load_dword v38, v14, s[8:9] offset:1536 nt
	global_load_dword v39, v15, s[8:9] offset:1536 nt
	global_load_dword v40, v16, s[8:9] offset:1536 nt
	global_load_dword v41, v17, s[8:9] offset:1536 nt
	global_load_dword v42, v18, s[8:9] offset:1536 nt
	global_load_dword v43, v19, s[8:9] offset:1536 nt
	global_load_dword v44, v20, s[8:9] offset:1536 nt
	global_load_dword v45, v21, s[8:9] offset:1536 nt
	global_load_dword v46, v22, s[8:9] offset:1536 nt
	global_load_dword v47, v23, s[8:9] offset:1536 nt
	s_waitcnt vmcnt(18)
	ds_write_b32 v3, v48 offset:16640
	ds_write_b32 v3, v49 offset:17680
	ds_write_b32 v3, v50 offset:18720
	ds_write_b32 v3, v51 offset:19760
	ds_write_b32 v3, v52 offset:20800
	ds_write_b32 v3, v53 offset:21840
	ds_write_b32 v3, v54 offset:22880
	ds_write_b32 v3, v55 offset:23920
	ds_write_b32 v3, v56 offset:24960
	ds_write_b32 v3, v57 offset:26000
	ds_write_b32 v3, v58 offset:27040
	ds_write_b32 v3, v59 offset:28080
	ds_write_b32 v3, v60 offset:29120
	ds_write_b32 v3, v61 offset:30160
	ds_write_b32 v3, v62 offset:31200
	ds_write_b32 v3, v63 offset:32240
	s_waitcnt lgkmcnt(0)
	s_barrier
	ds_read_b32 v64, v4 offset:16640
	ds_read_b32 v65, v4 offset:16900
	ds_read_b32 v66, v4 offset:17160
	ds_read_b32 v67, v4 offset:17420
	ds_read_b32 v68, v4 offset:17680
	ds_read_b32 v69, v4 offset:17940
	ds_read_b32 v70, v4 offset:18200
	ds_read_b32 v71, v4 offset:18460
	ds_read_b32 v72, v4 offset:24960
	ds_read_b32 v73, v4 offset:25220
	ds_read_b32 v74, v4 offset:25480
	ds_read_b32 v75, v4 offset:25740
	ds_read_b32 v76, v4 offset:26000
	ds_read_b32 v77, v4 offset:26260
	ds_read_b32 v78, v4 offset:26520
	ds_read_b32 v79, v4 offset:26780
	s_waitcnt lgkmcnt(0)
	v_cvt_pk_bf16_f32 v80, v64, v65
	v_cvt_pk_bf16_f32 v81, v66, v67
	v_cvt_pk_bf16_f32 v82, v68, v69
	v_cvt_pk_bf16_f32 v83, v70, v71
	v_cvt_pk_bf16_f32 v84, v72, v73
	v_cvt_pk_bf16_f32 v85, v74, v75
	v_cvt_pk_bf16_f32 v86, v76, v77
	v_cvt_pk_bf16_f32 v87, v78, v79
	global_store_dwordx4 v5, v[80:83], s[10:11] nt
	global_store_dwordx4 v5, v[84:87], s[10:11] offset:64 nt
	s_add_u32 s10, s10, 0x40000
	s_addc_u32 s11, s11, 0
	global_load_dword v48, v8, s[8:9] offset:1792 nt
	global_load_dword v49, v9, s[8:9] offset:1792 nt
	global_load_dword v50, v10, s[8:9] offset:1792 nt
	global_load_dword v51, v11, s[8:9] offset:1792 nt
	global_load_dword v52, v12, s[8:9] offset:1792 nt
	global_load_dword v53, v13, s[8:9] offset:1792 nt
	global_load_dword v54, v14, s[8:9] offset:1792 nt
	global_load_dword v55, v15, s[8:9] offset:1792 nt
	global_load_dword v56, v16, s[8:9] offset:1792 nt
	global_load_dword v57, v17, s[8:9] offset:1792 nt
	global_load_dword v58, v18, s[8:9] offset:1792 nt
	global_load_dword v59, v19, s[8:9] offset:1792 nt
	global_load_dword v60, v20, s[8:9] offset:1792 nt
	global_load_dword v61, v21, s[8:9] offset:1792 nt
	global_load_dword v62, v22, s[8:9] offset:1792 nt
	global_load_dword v63, v23, s[8:9] offset:1792 nt
	s_waitcnt vmcnt(18)
	ds_write_b32 v3, v32
	ds_write_b32 v3, v33 offset:1040
	ds_write_b32 v3, v34 offset:2080
	ds_write_b32 v3, v35 offset:3120
	ds_write_b32 v3, v36 offset:4160
	ds_write_b32 v3, v37 offset:5200
	ds_write_b32 v3, v38 offset:6240
	ds_write_b32 v3, v39 offset:7280
	ds_write_b32 v3, v40 offset:8320
	ds_write_b32 v3, v41 offset:9360
	ds_write_b32 v3, v42 offset:10400
	ds_write_b32 v3, v43 offset:11440
	ds_write_b32 v3, v44 offset:12480
	ds_write_b32 v3, v45 offset:13520
	ds_write_b32 v3, v46 offset:14560
	ds_write_b32 v3, v47 offset:15600
	s_waitcnt lgkmcnt(0)
	s_barrier
	ds_read_b32 v64, v4
	ds_read_b32 v65, v4 offset:260
	ds_read_b32 v66, v4 offset:520
	ds_read_b32 v67, v4 offset:780
	ds_read_b32 v68, v4 offset:1040
	ds_read_b32 v69, v4 offset:1300
	ds_read_b32 v70, v4 offset:1560
	ds_read_b32 v71, v4 offset:1820
	ds_read_b32 v72, v4 offset:8320
	ds_read_b32 v73, v4 offset:8580
	ds_read_b32 v74, v4 offset:8840
	ds_read_b32 v75, v4 offset:9100
	ds_read_b32 v76, v4 offset:9360
	ds_read_b32 v77, v4 offset:9620
	ds_read_b32 v78, v4 offset:9880
	ds_read_b32 v79, v4 offset:10140
	s_waitcnt lgkmcnt(0)
	v_cvt_pk_bf16_f32 v80, v64, v65
	v_cvt_pk_bf16_f32 v81, v66, v67
	v_cvt_pk_bf16_f32 v82, v68, v69
	v_cvt_pk_bf16_f32 v83, v70, v71
	v_cvt_pk_bf16_f32 v84, v72, v73
	v_cvt_pk_bf16_f32 v85, v74, v75
	v_cvt_pk_bf16_f32 v86, v76, v77
	v_cvt_pk_bf16_f32 v87, v78, v79
	global_store_dwordx4 v5, v[80:83], s[10:11] nt
	global_store_dwordx4 v5, v[84:87], s[10:11] offset:64 nt
	s_add_u32 s10, s10, 0x40000
	s_addc_u32 s11, s11, 0
	s_waitcnt vmcnt(2)
	ds_write_b32 v3, v48 offset:16640
	ds_write_b32 v3, v49 offset:17680
	ds_write_b32 v3, v50 offset:18720
	ds_write_b32 v3, v51 offset:19760
	ds_write_b32 v3, v52 offset:20800
	ds_write_b32 v3, v53 offset:21840
	ds_write_b32 v3, v54 offset:22880
	ds_write_b32 v3, v55 offset:23920
	ds_write_b32 v3, v56 offset:24960
	ds_write_b32 v3, v57 offset:26000
	ds_write_b32 v3, v58 offset:27040
	ds_write_b32 v3, v59 offset:28080
	ds_write_b32 v3, v60 offset:29120
	ds_write_b32 v3, v61 offset:30160
	ds_write_b32 v3, v62 offset:31200
	ds_write_b32 v3, v63 offset:32240
	s_waitcnt lgkmcnt(0)
	s_barrier
	ds_read_b32 v64, v4 offset:16640
	ds_read_b32 v65, v4 offset:16900
	ds_read_b32 v66, v4 offset:17160
	ds_read_b32 v67, v4 offset:17420
	ds_read_b32 v68, v4 offset:17680
	ds_read_b32 v69, v4 offset:17940
	ds_read_b32 v70, v4 offset:18200
	ds_read_b32 v71, v4 offset:18460
	ds_read_b32 v72, v4 offset:24960
	ds_read_b32 v73, v4 offset:25220
	ds_read_b32 v74, v4 offset:25480
	ds_read_b32 v75, v4 offset:25740
	ds_read_b32 v76, v4 offset:26000
	ds_read_b32 v77, v4 offset:26260
	ds_read_b32 v78, v4 offset:26520
	ds_read_b32 v79, v4 offset:26780
	s_waitcnt lgkmcnt(0)
	v_cvt_pk_bf16_f32 v80, v64, v65
	v_cvt_pk_bf16_f32 v81, v66, v67
	v_cvt_pk_bf16_f32 v82, v68, v69
	v_cvt_pk_bf16_f32 v83, v70, v71
	v_cvt_pk_bf16_f32 v84, v72, v73
	v_cvt_pk_bf16_f32 v85, v74, v75
	v_cvt_pk_bf16_f32 v86, v76, v77
	v_cvt_pk_bf16_f32 v87, v78, v79
	global_store_dwordx4 v5, v[80:83], s[10:11] nt
	global_store_dwordx4 v5, v[84:87], s[10:11] offset:64 nt
	s_branch .LBB0_431
.Ltrx_b:
	s_load_dwordx2 s[8:9], s[0:1], 0xc0
	s_sub_i32 s2, s2, 0x700
	s_and_b32 s3, s2, 7
	s_bfe_u32 s4, s2, 0x10003
	s_lshr_b32 s2, s2, 4
	s_waitcnt lgkmcnt(0)
	s_mul_i32 s0, s3, 0xe00000
	s_add_u32 s8, s8, s0
	s_addc_u32 s9, s9, 0
	s_lshl_b32 s0, s2, 18
	s_lshl_b32 s1, s4, 11
	s_add_u32 s0, s0, s1
	s_add_u32 s8, s8, s0
	s_addc_u32 s9, s9, 0
	s_add_u32 s10, s10, 0xa100000
	s_addc_u32 s11, s11, 0
	s_mul_i32 s0, s3, 0x700000
	s_lshl_b32 s1, s2, 7
	s_add_u32 s0, s0, s1
	s_mul_i32 s1, s4, 0x380000
	s_add_u32 s0, s0, s1
	s_add_u32 s10, s10, s0
	s_addc_u32 s11, s11, 0
	v_and_b32_e32 v1, 63, v216
	v_lshrrev_b32_e32 v2, 6, v216
	v_mul_u32_u24_e32 v3, 0x41, v2
	v_add_lshl_u32 v3, v3, v1, 2
	v_and_b32_e32 v6, 3, v216
	v_lshrrev_b32_e32 v7, 2, v216
	v_mul_u32_u24_e32 v4, 0x208, v6
	v_add_lshl_u32 v4, v4, v7, 2
	v_mul_u32_u24_e32 v5, 0x1c00, v7
	v_lshl_add_u32 v5, v6, 4, v5
	v_mul_u32_u24_e32 v8, 0x1000, v2
	v_lshl_add_u32 v8, v1, 2, v8
	v_add_u32_e32 v9, 0x4000, v8
	v_add_u32_e32 v10, 0x4000, v9
	v_add_u32_e32 v11, 0x4000, v10
	v_add_u32_e32 v12, 0x4000, v11
	v_add_u32_e32 v13, 0x4000, v12
	v_add_u32_e32 v14, 0x4000, v13
	v_add_u32_e32 v15, 0x4000, v14
	v_add_u32_e32 v16, 0x4000, v15
	v_add_u32_e32 v17, 0x4000, v16
	v_add_u32_e32 v18, 0x4000, v17
	v_add_u32_e32 v19, 0x4000, v18
	v_add_u32_e32 v20, 0x4000, v19
	v_add_u32_e32 v21, 0x4000, v20
	v_add_u32_e32 v22, 0x4000, v21
	v_add_u32_e32 v23, 0x4000, v22
	global_load_dword v32, v8, s[8:9] nt
	global_load_dword v33, v9, s[8:9] nt
	global_load_dword v34, v10, s[8:9] nt
	global_load_dword v35, v11, s[8:9] nt
	global_load_dword v36, v12, s[8:9] nt
	global_load_dword v37, v13, s[8:9] nt
	global_load_dword v38, v14, s[8:9] nt
	global_load_dword v39, v15, s[8:9] nt
	global_load_dword v40, v16, s[8:9] nt
	global_load_dword v41, v17, s[8:9] nt
	global_load_dword v42, v18, s[8:9] nt
	global_load_dword v43, v19, s[8:9] nt
	global_load_dword v44, v20, s[8:9] nt
	global_load_dword v45, v21, s[8:9] nt
	global_load_dword v46, v22, s[8:9] nt
	global_load_dword v47, v23, s[8:9] nt
	global_load_dword v48, v8, s[8:9] offset:256 nt
	global_load_dword v49, v9, s[8:9] offset:256 nt
	global_load_dword v50, v10, s[8:9] offset:256 nt
	global_load_dword v51, v11, s[8:9] offset:256 nt
	global_load_dword v52, v12, s[8:9] offset:256 nt
	global_load_dword v53, v13, s[8:9] offset:256 nt
	global_load_dword v54, v14, s[8:9] offset:256 nt
	global_load_dword v55, v15, s[8:9] offset:256 nt
	global_load_dword v56, v16, s[8:9] offset:256 nt
	global_load_dword v57, v17, s[8:9] offset:256 nt
	global_load_dword v58, v18, s[8:9] offset:256 nt
	global_load_dword v59, v19, s[8:9] offset:256 nt
	global_load_dword v60, v20, s[8:9] offset:256 nt
	global_load_dword v61, v21, s[8:9] offset:256 nt
	global_load_dword v62, v22, s[8:9] offset:256 nt
	global_load_dword v63, v23, s[8:9] offset:256 nt
	s_waitcnt vmcnt(16)
	ds_write_b32 v3, v32
	ds_write_b32 v3, v33 offset:1040
	ds_write_b32 v3, v34 offset:2080
	ds_write_b32 v3, v35 offset:3120
	ds_write_b32 v3, v36 offset:4160
	ds_write_b32 v3, v37 offset:5200
	ds_write_b32 v3, v38 offset:6240
	ds_write_b32 v3, v39 offset:7280
	ds_write_b32 v3, v40 offset:8320
	ds_write_b32 v3, v41 offset:9360
	ds_write_b32 v3, v42 offset:10400
	ds_write_b32 v3, v43 offset:11440
	ds_write_b32 v3, v44 offset:12480
	ds_write_b32 v3, v45 offset:13520
	ds_write_b32 v3, v46 offset:14560
	ds_write_b32 v3, v47 offset:15600
	s_waitcnt lgkmcnt(0)
	s_barrier
	ds_read_b32 v64, v4
	ds_read_b32 v65, v4 offset:260
	ds_read_b32 v66, v4 offset:520
	ds_read_b32 v67, v4 offset:780
	ds_read_b32 v68, v4 offset:1040
	ds_read_b32 v69, v4 offset:1300
	ds_read_b32 v70, v4 offset:1560
	ds_read_b32 v71, v4 offset:1820
	ds_read_b32 v72, v4 offset:8320
	ds_read_b32 v73, v4 offset:8580
	ds_read_b32 v74, v4 offset:8840
	ds_read_b32 v75, v4 offset:9100
	ds_read_b32 v76, v4 offset:9360
	ds_read_b32 v77, v4 offset:9620
	ds_read_b32 v78, v4 offset:9880
	ds_read_b32 v79, v4 offset:10140
	s_waitcnt lgkmcnt(0)
	v_cvt_pk_bf16_f32 v80, v64, v65
	v_cvt_pk_bf16_f32 v81, v66, v67
	v_cvt_pk_bf16_f32 v82, v68, v69
	v_cvt_pk_bf16_f32 v83, v70, v71
	v_cvt_pk_bf16_f32 v84, v72, v73
	v_cvt_pk_bf16_f32 v85, v74, v75
	v_cvt_pk_bf16_f32 v86, v76, v77
	v_cvt_pk_bf16_f32 v87, v78, v79
	global_store_dwordx4 v5, v[80:83], s[10:11] nt
	global_store_dwordx4 v5, v[84:87], s[10:11] offset:64 nt
	s_add_u32 s10, s10, 0x70000
	s_addc_u32 s11, s11, 0
	global_load_dword v32, v8, s[8:9] offset:512 nt
	global_load_dword v33, v9, s[8:9] offset:512 nt
	global_load_dword v34, v10, s[8:9] offset:512 nt
	global_load_dword v35, v11, s[8:9] offset:512 nt
	global_load_dword v36, v12, s[8:9] offset:512 nt
	global_load_dword v37, v13, s[8:9] offset:512 nt
	global_load_dword v38, v14, s[8:9] offset:512 nt
	global_load_dword v39, v15, s[8:9] offset:512 nt
	global_load_dword v40, v16, s[8:9] offset:512 nt
	global_load_dword v41, v17, s[8:9] offset:512 nt
	global_load_dword v42, v18, s[8:9] offset:512 nt
	global_load_dword v43, v19, s[8:9] offset:512 nt
	global_load_dword v44, v20, s[8:9] offset:512 nt
	global_load_dword v45, v21, s[8:9] offset:512 nt
	global_load_dword v46, v22, s[8:9] offset:512 nt
	global_load_dword v47, v23, s[8:9] offset:512 nt
	s_waitcnt vmcnt(18)
	ds_write_b32 v3, v48 offset:16640
	ds_write_b32 v3, v49 offset:17680
	ds_write_b32 v3, v50 offset:18720
	ds_write_b32 v3, v51 offset:19760
	ds_write_b32 v3, v52 offset:20800
	ds_write_b32 v3, v53 offset:21840
	ds_write_b32 v3, v54 offset:22880
	ds_write_b32 v3, v55 offset:23920
	ds_write_b32 v3, v56 offset:24960
	ds_write_b32 v3, v57 offset:26000
	ds_write_b32 v3, v58 offset:27040
	ds_write_b32 v3, v59 offset:28080
	ds_write_b32 v3, v60 offset:29120
	ds_write_b32 v3, v61 offset:30160
	ds_write_b32 v3, v62 offset:31200
	ds_write_b32 v3, v63 offset:32240
	s_waitcnt lgkmcnt(0)
	s_barrier
	ds_read_b32 v64, v4 offset:16640
	ds_read_b32 v65, v4 offset:16900
	ds_read_b32 v66, v4 offset:17160
	ds_read_b32 v67, v4 offset:17420
	ds_read_b32 v68, v4 offset:17680
	ds_read_b32 v69, v4 offset:17940
	ds_read_b32 v70, v4 offset:18200
	ds_read_b32 v71, v4 offset:18460
	ds_read_b32 v72, v4 offset:24960
	ds_read_b32 v73, v4 offset:25220
	ds_read_b32 v74, v4 offset:25480
	ds_read_b32 v75, v4 offset:25740
	ds_read_b32 v76, v4 offset:26000
	ds_read_b32 v77, v4 offset:26260
	ds_read_b32 v78, v4 offset:26520
	ds_read_b32 v79, v4 offset:26780
	s_waitcnt lgkmcnt(0)
	v_cvt_pk_bf16_f32 v80, v64, v65
	v_cvt_pk_bf16_f32 v81, v66, v67
	v_cvt_pk_bf16_f32 v82, v68, v69
	v_cvt_pk_bf16_f32 v83, v70, v71
	v_cvt_pk_bf16_f32 v84, v72, v73
	v_cvt_pk_bf16_f32 v85, v74, v75
	v_cvt_pk_bf16_f32 v86, v76, v77
	v_cvt_pk_bf16_f32 v87, v78, v79
	global_store_dwordx4 v5, v[80:83], s[10:11] nt
	global_store_dwordx4 v5, v[84:87], s[10:11] offset:64 nt
	s_add_u32 s10, s10, 0x70000
	s_addc_u32 s11, s11, 0
	global_load_dword v48, v8, s[8:9] offset:768 nt
	global_load_dword v49, v9, s[8:9] offset:768 nt
	global_load_dword v50, v10, s[8:9] offset:768 nt
	global_load_dword v51, v11, s[8:9] offset:768 nt
	global_load_dword v52, v12, s[8:9] offset:768 nt
	global_load_dword v53, v13, s[8:9] offset:768 nt
	global_load_dword v54, v14, s[8:9] offset:768 nt
	global_load_dword v55, v15, s[8:9] offset:768 nt
	global_load_dword v56, v16, s[8:9] offset:768 nt
	global_load_dword v57, v17, s[8:9] offset:768 nt
	global_load_dword v58, v18, s[8:9] offset:768 nt
	global_load_dword v59, v19, s[8:9] offset:768 nt
	global_load_dword v60, v20, s[8:9] offset:768 nt
	global_load_dword v61, v21, s[8:9] offset:768 nt
	global_load_dword v62, v22, s[8:9] offset:768 nt
	global_load_dword v63, v23, s[8:9] offset:768 nt
	s_waitcnt vmcnt(18)
	ds_write_b32 v3, v32
	ds_write_b32 v3, v33 offset:1040
	ds_write_b32 v3, v34 offset:2080
	ds_write_b32 v3, v35 offset:3120
	ds_write_b32 v3, v36 offset:4160
	ds_write_b32 v3, v37 offset:5200
	ds_write_b32 v3, v38 offset:6240
	ds_write_b32 v3, v39 offset:7280
	ds_write_b32 v3, v40 offset:8320
	ds_write_b32 v3, v41 offset:9360
	ds_write_b32 v3, v42 offset:10400
	ds_write_b32 v3, v43 offset:11440
	ds_write_b32 v3, v44 offset:12480
	ds_write_b32 v3, v45 offset:13520
	ds_write_b32 v3, v46 offset:14560
	ds_write_b32 v3, v47 offset:15600
	s_waitcnt lgkmcnt(0)
	s_barrier
	ds_read_b32 v64, v4
	ds_read_b32 v65, v4 offset:260
	ds_read_b32 v66, v4 offset:520
	ds_read_b32 v67, v4 offset:780
	ds_read_b32 v68, v4 offset:1040
	ds_read_b32 v69, v4 offset:1300
	ds_read_b32 v70, v4 offset:1560
	ds_read_b32 v71, v4 offset:1820
	ds_read_b32 v72, v4 offset:8320
	ds_read_b32 v73, v4 offset:8580
	ds_read_b32 v74, v4 offset:8840
	ds_read_b32 v75, v4 offset:9100
	ds_read_b32 v76, v4 offset:9360
	ds_read_b32 v77, v4 offset:9620
	ds_read_b32 v78, v4 offset:9880
	ds_read_b32 v79, v4 offset:10140
	s_waitcnt lgkmcnt(0)
	v_cvt_pk_bf16_f32 v80, v64, v65
	v_cvt_pk_bf16_f32 v81, v66, v67
	v_cvt_pk_bf16_f32 v82, v68, v69
	v_cvt_pk_bf16_f32 v83, v70, v71
	v_cvt_pk_bf16_f32 v84, v72, v73
	v_cvt_pk_bf16_f32 v85, v74, v75
	v_cvt_pk_bf16_f32 v86, v76, v77
	v_cvt_pk_bf16_f32 v87, v78, v79
	global_store_dwordx4 v5, v[80:83], s[10:11] nt
	global_store_dwordx4 v5, v[84:87], s[10:11] offset:64 nt
	s_add_u32 s10, s10, 0x70000
	s_addc_u32 s11, s11, 0
	global_load_dword v32, v8, s[8:9] offset:1024 nt
	global_load_dword v33, v9, s[8:9] offset:1024 nt
	global_load_dword v34, v10, s[8:9] offset:1024 nt
	global_load_dword v35, v11, s[8:9] offset:1024 nt
	global_load_dword v36, v12, s[8:9] offset:1024 nt
	global_load_dword v37, v13, s[8:9] offset:1024 nt
	global_load_dword v38, v14, s[8:9] offset:1024 nt
	global_load_dword v39, v15, s[8:9] offset:1024 nt
	global_load_dword v40, v16, s[8:9] offset:1024 nt
	global_load_dword v41, v17, s[8:9] offset:1024 nt
	global_load_dword v42, v18, s[8:9] offset:1024 nt
	global_load_dword v43, v19, s[8:9] offset:1024 nt
	global_load_dword v44, v20, s[8:9] offset:1024 nt
	global_load_dword v45, v21, s[8:9] offset:1024 nt
	global_load_dword v46, v22, s[8:9] offset:1024 nt
	global_load_dword v47, v23, s[8:9] offset:1024 nt
	s_waitcnt vmcnt(18)
	ds_write_b32 v3, v48 offset:16640
	ds_write_b32 v3, v49 offset:17680
	ds_write_b32 v3, v50 offset:18720
	ds_write_b32 v3, v51 offset:19760
	ds_write_b32 v3, v52 offset:20800
	ds_write_b32 v3, v53 offset:21840
	ds_write_b32 v3, v54 offset:22880
	ds_write_b32 v3, v55 offset:23920
	ds_write_b32 v3, v56 offset:24960
	ds_write_b32 v3, v57 offset:26000
	ds_write_b32 v3, v58 offset:27040
	ds_write_b32 v3, v59 offset:28080
	ds_write_b32 v3, v60 offset:29120
	ds_write_b32 v3, v61 offset:30160
	ds_write_b32 v3, v62 offset:31200
	ds_write_b32 v3, v63 offset:32240
	s_waitcnt lgkmcnt(0)
	s_barrier
	ds_read_b32 v64, v4 offset:16640
	ds_read_b32 v65, v4 offset:16900
	ds_read_b32 v66, v4 offset:17160
	ds_read_b32 v67, v4 offset:17420
	ds_read_b32 v68, v4 offset:17680
	ds_read_b32 v69, v4 offset:17940
	ds_read_b32 v70, v4 offset:18200
	ds_read_b32 v71, v4 offset:18460
	ds_read_b32 v72, v4 offset:24960
	ds_read_b32 v73, v4 offset:25220
	ds_read_b32 v74, v4 offset:25480
	ds_read_b32 v75, v4 offset:25740
	ds_read_b32 v76, v4 offset:26000
	ds_read_b32 v77, v4 offset:26260
	ds_read_b32 v78, v4 offset:26520
	ds_read_b32 v79, v4 offset:26780
	s_waitcnt lgkmcnt(0)
	v_cvt_pk_bf16_f32 v80, v64, v65
	v_cvt_pk_bf16_f32 v81, v66, v67
	v_cvt_pk_bf16_f32 v82, v68, v69
	v_cvt_pk_bf16_f32 v83, v70, v71
	v_cvt_pk_bf16_f32 v84, v72, v73
	v_cvt_pk_bf16_f32 v85, v74, v75
	v_cvt_pk_bf16_f32 v86, v76, v77
	v_cvt_pk_bf16_f32 v87, v78, v79
	global_store_dwordx4 v5, v[80:83], s[10:11] nt
	global_store_dwordx4 v5, v[84:87], s[10:11] offset:64 nt
	s_add_u32 s10, s10, 0x70000
	s_addc_u32 s11, s11, 0
	global_load_dword v48, v8, s[8:9] offset:1280 nt
	global_load_dword v49, v9, s[8:9] offset:1280 nt
	global_load_dword v50, v10, s[8:9] offset:1280 nt
	global_load_dword v51, v11, s[8:9] offset:1280 nt
	global_load_dword v52, v12, s[8:9] offset:1280 nt
	global_load_dword v53, v13, s[8:9] offset:1280 nt
	global_load_dword v54, v14, s[8:9] offset:1280 nt
	global_load_dword v55, v15, s[8:9] offset:1280 nt
	global_load_dword v56, v16, s[8:9] offset:1280 nt
	global_load_dword v57, v17, s[8:9] offset:1280 nt
	global_load_dword v58, v18, s[8:9] offset:1280 nt
	global_load_dword v59, v19, s[8:9] offset:1280 nt
	global_load_dword v60, v20, s[8:9] offset:1280 nt
	global_load_dword v61, v21, s[8:9] offset:1280 nt
	global_load_dword v62, v22, s[8:9] offset:1280 nt
	global_load_dword v63, v23, s[8:9] offset:1280 nt
	s_waitcnt vmcnt(18)
	ds_write_b32 v3, v32
	ds_write_b32 v3, v33 offset:1040
	ds_write_b32 v3, v34 offset:2080
	ds_write_b32 v3, v35 offset:3120
	ds_write_b32 v3, v36 offset:4160
	ds_write_b32 v3, v37 offset:5200
	ds_write_b32 v3, v38 offset:6240
	ds_write_b32 v3, v39 offset:7280
	ds_write_b32 v3, v40 offset:8320
	ds_write_b32 v3, v41 offset:9360
	ds_write_b32 v3, v42 offset:10400
	ds_write_b32 v3, v43 offset:11440
	ds_write_b32 v3, v44 offset:12480
	ds_write_b32 v3, v45 offset:13520
	ds_write_b32 v3, v46 offset:14560
	ds_write_b32 v3, v47 offset:15600
	s_waitcnt lgkmcnt(0)
	s_barrier
	ds_read_b32 v64, v4
	ds_read_b32 v65, v4 offset:260
	ds_read_b32 v66, v4 offset:520
	ds_read_b32 v67, v4 offset:780
	ds_read_b32 v68, v4 offset:1040
	ds_read_b32 v69, v4 offset:1300
	ds_read_b32 v70, v4 offset:1560
	ds_read_b32 v71, v4 offset:1820
	ds_read_b32 v72, v4 offset:8320
	ds_read_b32 v73, v4 offset:8580
	ds_read_b32 v74, v4 offset:8840
	ds_read_b32 v75, v4 offset:9100
	ds_read_b32 v76, v4 offset:9360
	ds_read_b32 v77, v4 offset:9620
	ds_read_b32 v78, v4 offset:9880
	ds_read_b32 v79, v4 offset:10140
	s_waitcnt lgkmcnt(0)
	v_cvt_pk_bf16_f32 v80, v64, v65
	v_cvt_pk_bf16_f32 v81, v66, v67
	v_cvt_pk_bf16_f32 v82, v68, v69
	v_cvt_pk_bf16_f32 v83, v70, v71
	v_cvt_pk_bf16_f32 v84, v72, v73
	v_cvt_pk_bf16_f32 v85, v74, v75
	v_cvt_pk_bf16_f32 v86, v76, v77
	v_cvt_pk_bf16_f32 v87, v78, v79
	global_store_dwordx4 v5, v[80:83], s[10:11] nt
	global_store_dwordx4 v5, v[84:87], s[10:11] offset:64 nt
	s_add_u32 s10, s10, 0x70000
	s_addc_u32 s11, s11, 0
	global_load_dword v32, v8, s[8:9] offset:1536 nt
	global_load_dword v33, v9, s[8:9] offset:1536 nt
	global_load_dword v34, v10, s[8:9] offset:1536 nt
	global_load_dword v35, v11, s[8:9] offset:1536 nt
	global_load_dword v36, v12, s[8:9] offset:1536 nt
	global_load_dword v37, v13, s[8:9] offset:1536 nt
	global_load_dword v38, v14, s[8:9] offset:1536 nt
	global_load_dword v39, v15, s[8:9] offset:1536 nt
	global_load_dword v40, v16, s[8:9] offset:1536 nt
	global_load_dword v41, v17, s[8:9] offset:1536 nt
	global_load_dword v42, v18, s[8:9] offset:1536 nt
	global_load_dword v43, v19, s[8:9] offset:1536 nt
	global_load_dword v44, v20, s[8:9] offset:1536 nt
	global_load_dword v45, v21, s[8:9] offset:1536 nt
	global_load_dword v46, v22, s[8:9] offset:1536 nt
	global_load_dword v47, v23, s[8:9] offset:1536 nt
	s_waitcnt vmcnt(18)
	ds_write_b32 v3, v48 offset:16640
	ds_write_b32 v3, v49 offset:17680
	ds_write_b32 v3, v50 offset:18720
	ds_write_b32 v3, v51 offset:19760
	ds_write_b32 v3, v52 offset:20800
	ds_write_b32 v3, v53 offset:21840
	ds_write_b32 v3, v54 offset:22880
	ds_write_b32 v3, v55 offset:23920
	ds_write_b32 v3, v56 offset:24960
	ds_write_b32 v3, v57 offset:26000
	ds_write_b32 v3, v58 offset:27040
	ds_write_b32 v3, v59 offset:28080
	ds_write_b32 v3, v60 offset:29120
	ds_write_b32 v3, v61 offset:30160
	ds_write_b32 v3, v62 offset:31200
	ds_write_b32 v3, v63 offset:32240
	s_waitcnt lgkmcnt(0)
	s_barrier
	ds_read_b32 v64, v4 offset:16640
	ds_read_b32 v65, v4 offset:16900
	ds_read_b32 v66, v4 offset:17160
	ds_read_b32 v67, v4 offset:17420
	ds_read_b32 v68, v4 offset:17680
	ds_read_b32 v69, v4 offset:17940
	ds_read_b32 v70, v4 offset:18200
	ds_read_b32 v71, v4 offset:18460
	ds_read_b32 v72, v4 offset:24960
	ds_read_b32 v73, v4 offset:25220
	ds_read_b32 v74, v4 offset:25480
	ds_read_b32 v75, v4 offset:25740
	ds_read_b32 v76, v4 offset:26000
	ds_read_b32 v77, v4 offset:26260
	ds_read_b32 v78, v4 offset:26520
	ds_read_b32 v79, v4 offset:26780
	s_waitcnt lgkmcnt(0)
	v_cvt_pk_bf16_f32 v80, v64, v65
	v_cvt_pk_bf16_f32 v81, v66, v67
	v_cvt_pk_bf16_f32 v82, v68, v69
	v_cvt_pk_bf16_f32 v83, v70, v71
	v_cvt_pk_bf16_f32 v84, v72, v73
	v_cvt_pk_bf16_f32 v85, v74, v75
	v_cvt_pk_bf16_f32 v86, v76, v77
	v_cvt_pk_bf16_f32 v87, v78, v79
	global_store_dwordx4 v5, v[80:83], s[10:11] nt
	global_store_dwordx4 v5, v[84:87], s[10:11] offset:64 nt
	s_add_u32 s10, s10, 0x70000
	s_addc_u32 s11, s11, 0
	global_load_dword v48, v8, s[8:9] offset:1792 nt
	global_load_dword v49, v9, s[8:9] offset:1792 nt
	global_load_dword v50, v10, s[8:9] offset:1792 nt
	global_load_dword v51, v11, s[8:9] offset:1792 nt
	global_load_dword v52, v12, s[8:9] offset:1792 nt
	global_load_dword v53, v13, s[8:9] offset:1792 nt
	global_load_dword v54, v14, s[8:9] offset:1792 nt
	global_load_dword v55, v15, s[8:9] offset:1792 nt
	global_load_dword v56, v16, s[8:9] offset:1792 nt
	global_load_dword v57, v17, s[8:9] offset:1792 nt
	global_load_dword v58, v18, s[8:9] offset:1792 nt
	global_load_dword v59, v19, s[8:9] offset:1792 nt
	global_load_dword v60, v20, s[8:9] offset:1792 nt
	global_load_dword v61, v21, s[8:9] offset:1792 nt
	global_load_dword v62, v22, s[8:9] offset:1792 nt
	global_load_dword v63, v23, s[8:9] offset:1792 nt
	s_waitcnt vmcnt(18)
	ds_write_b32 v3, v32
	ds_write_b32 v3, v33 offset:1040
	ds_write_b32 v3, v34 offset:2080
	ds_write_b32 v3, v35 offset:3120
	ds_write_b32 v3, v36 offset:4160
	ds_write_b32 v3, v37 offset:5200
	ds_write_b32 v3, v38 offset:6240
	ds_write_b32 v3, v39 offset:7280
	ds_write_b32 v3, v40 offset:8320
	ds_write_b32 v3, v41 offset:9360
	ds_write_b32 v3, v42 offset:10400
	ds_write_b32 v3, v43 offset:11440
	ds_write_b32 v3, v44 offset:12480
	ds_write_b32 v3, v45 offset:13520
	ds_write_b32 v3, v46 offset:14560
	ds_write_b32 v3, v47 offset:15600
	s_waitcnt lgkmcnt(0)
	s_barrier
	ds_read_b32 v64, v4
	ds_read_b32 v65, v4 offset:260
	ds_read_b32 v66, v4 offset:520
	ds_read_b32 v67, v4 offset:780
	ds_read_b32 v68, v4 offset:1040
	ds_read_b32 v69, v4 offset:1300
	ds_read_b32 v70, v4 offset:1560
	ds_read_b32 v71, v4 offset:1820
	ds_read_b32 v72, v4 offset:8320
	ds_read_b32 v73, v4 offset:8580
	ds_read_b32 v74, v4 offset:8840
	ds_read_b32 v75, v4 offset:9100
	ds_read_b32 v76, v4 offset:9360
	ds_read_b32 v77, v4 offset:9620
	ds_read_b32 v78, v4 offset:9880
	ds_read_b32 v79, v4 offset:10140
	s_waitcnt lgkmcnt(0)
	v_cvt_pk_bf16_f32 v80, v64, v65
	v_cvt_pk_bf16_f32 v81, v66, v67
	v_cvt_pk_bf16_f32 v82, v68, v69
	v_cvt_pk_bf16_f32 v83, v70, v71
	v_cvt_pk_bf16_f32 v84, v72, v73
	v_cvt_pk_bf16_f32 v85, v74, v75
	v_cvt_pk_bf16_f32 v86, v76, v77
	v_cvt_pk_bf16_f32 v87, v78, v79
	global_store_dwordx4 v5, v[80:83], s[10:11] nt
	global_store_dwordx4 v5, v[84:87], s[10:11] offset:64 nt
	s_add_u32 s10, s10, 0x70000
	s_addc_u32 s11, s11, 0
	s_waitcnt vmcnt(2)
	ds_write_b32 v3, v48 offset:16640
	ds_write_b32 v3, v49 offset:17680
	ds_write_b32 v3, v50 offset:18720
	ds_write_b32 v3, v51 offset:19760
	ds_write_b32 v3, v52 offset:20800
	ds_write_b32 v3, v53 offset:21840
	ds_write_b32 v3, v54 offset:22880
	ds_write_b32 v3, v55 offset:23920
	ds_write_b32 v3, v56 offset:24960
	ds_write_b32 v3, v57 offset:26000
	ds_write_b32 v3, v58 offset:27040
	ds_write_b32 v3, v59 offset:28080
	ds_write_b32 v3, v60 offset:29120
	ds_write_b32 v3, v61 offset:30160
	ds_write_b32 v3, v62 offset:31200
	ds_write_b32 v3, v63 offset:32240
	s_waitcnt lgkmcnt(0)
	s_barrier
	ds_read_b32 v64, v4 offset:16640
	ds_read_b32 v65, v4 offset:16900
	ds_read_b32 v66, v4 offset:17160
	ds_read_b32 v67, v4 offset:17420
	ds_read_b32 v68, v4 offset:17680
	ds_read_b32 v69, v4 offset:17940
	ds_read_b32 v70, v4 offset:18200
	ds_read_b32 v71, v4 offset:18460
	ds_read_b32 v72, v4 offset:24960
	ds_read_b32 v73, v4 offset:25220
	ds_read_b32 v74, v4 offset:25480
	ds_read_b32 v75, v4 offset:25740
	ds_read_b32 v76, v4 offset:26000
	ds_read_b32 v77, v4 offset:26260
	ds_read_b32 v78, v4 offset:26520
	ds_read_b32 v79, v4 offset:26780
	s_waitcnt lgkmcnt(0)
	v_cvt_pk_bf16_f32 v80, v64, v65
	v_cvt_pk_bf16_f32 v81, v66, v67
	v_cvt_pk_bf16_f32 v82, v68, v69
	v_cvt_pk_bf16_f32 v83, v70, v71
	v_cvt_pk_bf16_f32 v84, v72, v73
	v_cvt_pk_bf16_f32 v85, v74, v75
	v_cvt_pk_bf16_f32 v86, v76, v77
	v_cvt_pk_bf16_f32 v87, v78, v79
	global_store_dwordx4 v5, v[80:83], s[10:11] nt
	global_store_dwordx4 v5, v[84:87], s[10:11] offset:64 nt
	s_branch .LBB0_431

.LBB0_437:
	s_or_b64 exec, exec, s[2:3]
	s_waitcnt lgkmcnt(0)
	s_barrier
	ds_read_b32 v0, v221
	s_movk_i32 s2, 0x105f
	s_waitcnt lgkmcnt(0)
	s_barrier
	v_cmp_lt_i32_e32 vcc, s2, v0
	v_readfirstlane_b32 s95, v0
	s_mov_b64 s[2:3], -1
	s_cbranch_vccnz .LBB0_432
	s_cmpk_gt_i32 s95, 0xb1f
	s_cbranch_scc1 .Ltrx_item
	s_cmp_gt_i32 s95, 31
	s_cbranch_scc0 .LBB0_497
	s_cmpk_gt_u32 s95, 0x21f
	s_cbranch_scc0 .LBB0_483
	s_add_i32 s2, s95, 0xfde0
	s_and_b32 s3, s2, 0xffff
	s_mul_i32 s3, s3, 0xaaab
	s_lshr_b32 s26, s3, 25
	s_mul_i32 s3, s26, 0x300
	s_sub_i32 s2, s2, s3
	s_and_b32 s4, s2, 0xffff
	s_bfe_u32 s3, s2, 0xc0004
	s_mul_i32 s4, s4, 0xaaab
	s_lshr_b32 s47, s4, 22
	s_mul_i32 s4, s3, 0xab
	s_bfe_u32 s4, s4, 0x6000a
	v_readlane_b32 s8, v254, 45
	s_mul_i32 s4, s4, 6
	v_readlane_b32 s11, v254, 48
	s_sub_i32 s3, s3, s4
	s_lshl_b32 s11, s26, 1
	s_and_b32 s4, s3, 0xff
	s_lshr_b32 s3, 64, s11
	s_lshl_b32 s2, s2, 2
	v_readlane_b32 s12, v254, 49
	s_and_b32 s2, s2, 60
	s_sub_i32 s8, 6, s11
	s_add_i32 s3, s3, -1
	v_readlane_b32 s10, v254, 47
	v_readlane_b32 s14, v254, 51
	v_readlane_b32 s15, v254, 52
	s_lshr_b32 s12, s2, s8
	s_and_b32 s2, s3, s2
	v_mov_b32_e32 v6, v216
	v_readlane_b32 s13, v254, 50
	v_mov_b32_e32 v0, s14
	v_mov_b32_e32 v1, s15
	s_lshl_b32 s10, s2, 5
	s_mul_i32 s2, s47, 0xc0000
	s_lshl_b32 s13, s2, 1
	v_readfirstlane_b32 s5, v0
	v_readfirstlane_b32 s46, v1
	s_add_u32 s2, s5, s13
	s_addc_u32 s3, s46, 0
	s_lshl_b32 s8, s4, 7
	s_add_u32 s2, s2, s8
	v_lshlrev_b32_e32 v7, 4, v6
	s_addc_u32 s3, s3, 0
	v_and_b32_e32 v0, 0x70, v7
	v_mov_b32_e32 v1, v179
	s_add_i32 s14, s10, 0xffffff80
	v_lshl_add_u64 v[2:3], s[2:3], 0, v[0:1]
	v_ashrrev_i32_e32 v1, 3, v6
	s_mov_b64 s[2:3], 0x1f622100
	v_add_u32_e32 v4, s14, v1
	v_lshl_add_u64 v[2:3], v[2:3], 0, s[2:3]
	v_cmp_lt_i32_e32 vcc, -1, v4
	v_readlane_b32 s9, v254, 46
	s_and_saveexec_b64 s[2:3], vcc
	s_cbranch_execz .LBB0_442
	v_lshlrev_b32_e32 v4, s11, v4
	v_add_u32_e32 v4, s12, v4
	v_mad_u64_u32 v[4:5], s[8:9], v4, s69, v[2:3]
	global_load_dwordx4 v[8:11], v[4:5], off
	v_mad_u64_u32 v[4:5], s[8:9], v1, s97, v[0:1]
	s_waitcnt vmcnt(0)
	ds_write_b128 v4, v[8:11]
